# weight conversion spread over idle workgroups of the adaLN, QKV(l0) and SGU-in(l1) GEMM phases; phase 0 converts w_ada only
# speedup vs baseline: 1.0260x; 1.0047x over previous
.LBB0_243:
	s_waitcnt vmcnt(0)
	v_readlane_b32 s25, v253, 41
	s_barrier
	v_readlane_b32 s2, v252, 3
	s_cmp_lg_u32 s2, 12
	s_cbranch_scc1 .LBB0_244
	s_cmpk_lt_i32 s84, 0x40
	s_cbranch_scc1 .LBB0_244
	v_readlane_b32 s2, v253, 30
	s_add_i32 s3, s84, 0xffffffc0
	s_lshl_b32 s3, s3, 3
	s_add_i32 s3, s3, s2
	s_add_i32 s58, s3, 0x5d00
	s_movk_i32 s40, 0xc0
	s_movk_i32 s70, 0x600
	s_mov_b32 s60, 0x7dff
	s_mov_b32 s61, 0x7e00
	s_mov_b32 s71, 6
	s_load_dwordx2 s[82:83], s[54:55], 0xe0
	s_branch .Ldef_common

.LBB0_569:
	s_waitcnt vmcnt(0)
	v_readlane_b32 s70, v253, 32
	v_readlane_b32 s71, v253, 33
	v_readlane_b32 s72, v253, 34
	v_readlane_b32 s74, v253, 36
	s_movk_i32 s67, 0x82
	s_mov_b32 s68, 0xc0135761
	s_mov_b32 s69, s79
	v_readlane_b32 s73, v253, 35
	v_readlane_b32 s75, v253, 37
	v_readlane_b32 s71, v253, 38
	v_readlane_b32 s25, v253, 41
	s_barrier
	v_readlane_b32 s2, v252, 3
	s_cmp_lg_u32 s2, 3
	s_cbranch_scc1 .LBB0_570
	s_cmpk_lt_i32 s84, 0x98
	s_cbranch_scc1 .LBB0_570
	v_readlane_b32 s2, v253, 30
	s_add_i32 s3, s84, 0xffffff68
	s_lshl_b32 s3, s3, 3
	s_add_i32 s3, s3, s2
	s_add_i32 s58, s3, 0x7e00
	s_movk_i32 s40, 0x68
	s_movk_i32 s70, 0x340
	s_mov_b32 s60, 0x93ff
	s_mov_b32 s61, 0x9400
	s_load_dwordx2 s[82:83], s[54:55], 0xe0
	s_branch .Ldef_common

.LBB0_635:
	s_andn2_b64 vcc, exec, s[2:3]
	s_cbranch_vccz .Lada_has_tile
	v_readlane_b32 s2, v253, 30
	s_add_i32 s3, s84, 0xffffffa0
	s_lshl_b32 s3, s3, 3
	s_add_i32 s3, s3, s2
	s_add_i32 s58, s3, 0x3000
	s_movk_i32 s40, 0xa0
	s_movk_i32 s70, 0x500
	s_mov_b32 s60, 0x5cff
	s_mov_b32 s61, 0x5d00
	s_branch .Ldef_common

.LBB0_668:
	s_and_b64 vcc, exec, s[2:3]
	s_cbranch_vccz .LBB0_763
	s_mov_b32 s60, 0x2fff
	s_mov_b32 s61, 0x3000

.LBB0_728:
	s_cmp_lg_u32 s71, 0
	s_cbranch_scc1 .LBB0_763
	v_lshl_or_b32 v2, s58, 6, v233
	s_mov_b32 s3, 0x10040
	s_lshl_b32 s2, s40, 9
	v_cmp_gt_i32_e32 vcc, s3, v2
	v_and_b32_e32 v5, 7, v241
	s_and_saveexec_b64 s[4:5], vcc
	s_cbranch_execz .LBB0_731
	v_lshlrev_b32_e32 v0, 3, v5
	s_waitcnt lgkmcnt(0)
	global_load_dwordx2 v[6:7], v0, s[54:55] offset:232
	s_add_u32 s6, s82, 0x100000
	s_addc_u32 s7, s83, 0
	s_mov_b64 s[8:9], 0
	v_mov_b32_e32 v0, v2
	s_waitcnt vmcnt(0)
